# ret_out epilogue: gate loads + GY stores further widened to 64-B row segments (adjacent-row DPP exchange on top of permlane32 pairs), 4 quads in flight
# baseline (speedup 1.0000x reference)
; __device__ __forceinline__ unsigned cvtpk(float lo, float hi) { return pg8::cvt_pk_bf16(lo, hi); }
;     ...
;         { R2_IDS const float rstd = 1.0f / sqrtf((ssp[32 * nt + r] + ssp[128 + 32 * nt + r]) * (1.0f / 512.0f) + RMS_EPS);
;           bf16* gp = GY + ((size_t)((bh >> 2) * SEQ + tq0 + 32 * nt + r)) * 2048 + h * 512 + 256 * eh + 4 * hh;
; #pragma unroll
;           for (int et = 0; et < 8; ++et)
; #pragma unroll
;               for (int i4 = 0; i4 < 4; ++i4) { bf16* p4 = gp + 32 * et + 8 * i4; const v2u gg = *(const v2u*)p4;
;                   v2u wv; wv.x = cvtpk(acc[et][4 * i4] * rstd * __uint_as_float(gg.x << 16), acc[et][4 * i4 + 1] * rstd * __uint_as_float(gg.x & 0xffff0000u));
;                   wv.y = cvtpk(acc[et][4 * i4 + 2] * rstd * __uint_as_float(gg.y << 16), acc[et][4 * i4 + 3] * rstd * __uint_as_float(gg.y & 0xffff0000u));
;                   if (!dry || rstd == 1.2345e38f) *(v2u*)p4 = wv; if (i4 == 3 && (et & 1)) asm volatile("" ::: "memory"); } }
.LBB0_717:
	s_or_b64 exec, exec, s[6:7]
	s_lshl_b32 s6, s36, 5
	s_and_b32 s6, s6, 0xffffe000
	v_mov_b32_e32 v52, v33
	s_add_i32 s5, s5, s6
	s_waitcnt lgkmcnt(0)
	s_barrier
	s_or_b32 s5, s5, s47
	s_waitcnt vmcnt(2)
	v_and_b32_e32 v56, 31, v52
	v_or_b32_e32 v50, s5, v56
	v_ashrrev_i32_e32 v51, 31, v50
	v_lshlrev_b64 v[50:51], 12, v[50:51]
	v_lshl_add_u64 v[50:51], s[28:29], 0, v[50:51]
	s_lshl_b32 s94, s4, 10
	v_lshl_add_u64 v[50:51], v[50:51], 0, s[94:95]
	v_lshrrev_b32_e32 v52, 2, v52
	v_lshl_add_u64 v[50:51], s[30:31], 1, v[50:51]
	v_and_b32_e32 v52, 8, v52
	v_lshlrev_b32_e32 v52, 1, v52
	v_mov_b32_e32 v53, v32
	v_lshl_add_u64 v[50:51], v[50:51], 0, v[52:53]
	v_and_b32_e32 v230, 1, v228
	v_sub_u32_e32 v230, 0, v230
	v_and_b32_e32 v52, 0xfffff020, v230
	v_add_u32_e32 v52, 0x800, v52
	v_mov_b32_e32 v53, v230
	v_lshl_add_u64 v[50:51], v[50:51], 0, v[52:53]
	global_load_dwordx4 v[82:85], v[50:51], off offset:-2048
	global_load_dwordx4 v[86:89], v[50:51], off offset:2048
	global_load_dwordx4 v[90:93], v[50:51], off offset:-1984
	global_load_dwordx4 v[204:207], v[50:51], off offset:2112
	global_load_dwordx4 v[208:211], v[50:51], off offset:-1920
	global_load_dwordx4 v[212:215], v[50:51], off offset:2176
	global_load_dwordx4 v[216:219], v[50:51], off offset:-1856
	global_load_dwordx4 v[220:223], v[50:51], off offset:2240
	v_lshl_add_u32 v52, v56, 2, s50
	ds_read2st64_b32 v[52:53], v52 offset1:2
	s_add_i32 s36, s36, s48
	s_cmpk_lt_i32 s36, 0x200
	s_waitcnt lgkmcnt(0)
	v_add_f32_e32 v52, v52, v53
	v_fmamk_f32 v52, v52, 0x3b000000, v231
	v_mul_f32_e32 v53, 0x4f800000, v52
	v_cmp_gt_f32_e32 vcc, s73, v52
	s_nop 1
	v_cndmask_b32_e32 v52, v52, v53, vcc
	v_sqrt_f32_e32 v53, v52
	s_nop 0
	v_add_u32_e32 v56, -1, v53
	v_add_u32_e32 v57, 1, v53
	v_fma_f32 v58, -v56, v53, v52
	v_fma_f32 v59, -v57, v53, v52
	v_cmp_ge_f32_e64 s[40:41], 0, v58
	s_nop 1
	v_cndmask_b32_e64 v53, v53, v56, s[40:41]
	v_cmp_lt_f32_e64 s[40:41], 0, v59
	s_nop 1
	v_cndmask_b32_e64 v53, v53, v57, s[40:41]
	v_mul_f32_e32 v56, 0x37800000, v53
	v_cndmask_b32_e32 v53, v53, v56, vcc
	v_cmp_class_f32_e32 vcc, v52, v232
	s_nop 1
	v_cndmask_b32_e32 v52, v53, v52, vcc
	v_div_scale_f32 v53, s[4:5], v52, v52, 1.0
	v_rcp_f32_e32 v56, v53
	v_div_scale_f32 v57, vcc, 1.0, v52, 1.0
	v_fma_f32 v58, -v53, v56, 1.0
	v_fmac_f32_e32 v56, v58, v56
	v_mul_f32_e32 v58, v57, v56
	v_fma_f32 v59, -v53, v58, v57
	v_fmac_f32_e32 v58, v59, v56
	v_fma_f32 v53, -v53, v58, v57
	v_div_fmas_f32 v53, v53, v56, v58
	v_div_fixup_f32 v52, v53, v52, 1.0
	s_waitcnt vmcnt(6)
	v_bfi_b32 v238, v230, v82, v86
	v_bfi_b32 v239, v230, v83, v87
	v_bfi_b32 v240, v230, v84, v88
	v_bfi_b32 v241, v230, v85, v89
	v_mov_b32_dpp v242, v238 quad_perm:[1,0,3,2] row_mask:0xf bank_mask:0xf
	v_mov_b32_dpp v243, v239 quad_perm:[1,0,3,2] row_mask:0xf bank_mask:0xf
	v_mov_b32_dpp v244, v240 quad_perm:[1,0,3,2] row_mask:0xf bank_mask:0xf
	v_mov_b32_dpp v245, v241 quad_perm:[1,0,3,2] row_mask:0xf bank_mask:0xf
	v_bfi_b32 v82, v230, v242, v82
	v_bfi_b32 v83, v230, v243, v83
	v_bfi_b32 v84, v230, v244, v84
	v_bfi_b32 v85, v230, v245, v85
	v_bfi_b32 v86, v230, v86, v242
	v_bfi_b32 v87, v230, v87, v243
	v_bfi_b32 v88, v230, v88, v244
	v_bfi_b32 v89, v230, v89, v245
	v_permlane32_swap_b32_e32 v82, v84
	v_permlane32_swap_b32_e32 v83, v85
	v_permlane32_swap_b32_e32 v86, v88
	v_permlane32_swap_b32_e32 v87, v89
	v_lshlrev_b32_e32 v57, 16, v82
	v_and_b32_e32 v58, 0xffff0000, v82
	v_lshlrev_b32_e32 v59, 16, v83
	v_and_b32_e32 v60, 0xffff0000, v83
	v_mul_f32_e32 v53, v178, v52
	v_mul_f32_e32 v54, v179, v52
	v_mul_f32_e32 v55, v180, v52
	v_mul_f32_e32 v56, v181, v52
	v_mul_f32_e32 v53, v53, v57
	v_mul_f32_e32 v54, v54, v58
	v_mul_f32_e32 v55, v55, v59
	v_mul_f32_e32 v56, v56, v60
	v_cvt_pk_bf16_f32 v250, v53, v54
	v_cvt_pk_bf16_f32 v251, v55, v56
	v_lshlrev_b32_e32 v57, 16, v84
	v_and_b32_e32 v58, 0xffff0000, v84
	v_lshlrev_b32_e32 v59, 16, v85
	v_and_b32_e32 v60, 0xffff0000, v85
	v_mul_f32_e32 v53, v182, v52
	v_mul_f32_e32 v54, v183, v52
	v_mul_f32_e32 v55, v184, v52
	v_mul_f32_e32 v56, v185, v52
	v_mul_f32_e32 v53, v53, v57
	v_mul_f32_e32 v54, v54, v58
	v_mul_f32_e32 v55, v55, v59
	v_mul_f32_e32 v56, v56, v60
	v_cvt_pk_bf16_f32 v252, v53, v54
	v_cvt_pk_bf16_f32 v253, v55, v56
	v_lshlrev_b32_e32 v57, 16, v86
	v_and_b32_e32 v58, 0xffff0000, v86
	v_lshlrev_b32_e32 v59, 16, v87
	v_and_b32_e32 v60, 0xffff0000, v87
	v_mul_f32_e32 v53, v186, v52
	v_mul_f32_e32 v54, v187, v52
	v_mul_f32_e32 v55, v188, v52
	v_mul_f32_e32 v56, v189, v52
	v_mul_f32_e32 v53, v53, v57
	v_mul_f32_e32 v54, v54, v58
	v_mul_f32_e32 v55, v55, v59
	v_mul_f32_e32 v56, v56, v60
	v_cvt_pk_bf16_f32 v224, v53, v54
	v_cvt_pk_bf16_f32 v225, v55, v56
	v_lshlrev_b32_e32 v57, 16, v88
	v_and_b32_e32 v58, 0xffff0000, v88
	v_lshlrev_b32_e32 v59, 16, v89
	v_and_b32_e32 v60, 0xffff0000, v89
	v_mul_f32_e32 v53, v190, v52
	v_mul_f32_e32 v54, v191, v52
	v_mul_f32_e32 v55, v192, v52
	v_mul_f32_e32 v56, v193, v52
	v_mul_f32_e32 v53, v53, v57
	v_mul_f32_e32 v54, v54, v58
	v_mul_f32_e32 v55, v55, v59
	v_mul_f32_e32 v56, v56, v60
	v_cvt_pk_bf16_f32 v226, v53, v54
	v_cvt_pk_bf16_f32 v227, v55, v56
	s_nop 0
	v_permlane32_swap_b32_e32 v250, v252
	v_permlane32_swap_b32_e32 v251, v253
	v_permlane32_swap_b32_e32 v224, v226
	v_permlane32_swap_b32_e32 v225, v227
	v_bfi_b32 v238, v230, v250, v224
	v_bfi_b32 v239, v230, v251, v225
	v_bfi_b32 v240, v230, v252, v226
	v_bfi_b32 v241, v230, v253, v227
	v_mov_b32_dpp v242, v238 quad_perm:[1,0,3,2] row_mask:0xf bank_mask:0xf
	v_mov_b32_dpp v243, v239 quad_perm:[1,0,3,2] row_mask:0xf bank_mask:0xf
	v_mov_b32_dpp v244, v240 quad_perm:[1,0,3,2] row_mask:0xf bank_mask:0xf
	v_mov_b32_dpp v245, v241 quad_perm:[1,0,3,2] row_mask:0xf bank_mask:0xf
	v_bfi_b32 v250, v230, v242, v250
	v_bfi_b32 v251, v230, v243, v251
	v_bfi_b32 v252, v230, v244, v252
	v_bfi_b32 v253, v230, v245, v253
	v_bfi_b32 v242, v230, v224, v242
	v_bfi_b32 v243, v230, v225, v243
	v_bfi_b32 v244, v230, v226, v244
	v_bfi_b32 v245, v230, v227, v245
	global_store_dwordx4 v[50:51], v[250:253], off offset:-2048
	global_store_dwordx4 v[50:51], v[242:245], off offset:2048
	global_load_dwordx4 v[82:85], v[50:51], off offset:-1792
	global_load_dwordx4 v[86:89], v[50:51], off offset:2304
	s_waitcnt vmcnt(8)
; __device__ __forceinline__ unsigned cvtpk(float lo, float hi) { return pg8::cvt_pk_bf16(lo, hi); }
;     ...
;         { R2_IDS const float rstd = 1.0f / sqrtf((ssp[32 * nt + r] + ssp[128 + 32 * nt + r]) * (1.0f / 512.0f) + RMS_EPS);
;           bf16* gp = GY + ((size_t)((bh >> 2) * SEQ + tq0 + 32 * nt + r)) * 2048 + h * 512 + 256 * eh + 4 * hh;
; #pragma unroll
;           for (int et = 0; et < 8; ++et)
; #pragma unroll
;               for (int i4 = 0; i4 < 4; ++i4) { bf16* p4 = gp + 32 * et + 8 * i4; const v2u gg = *(const v2u*)p4;
;                   v2u wv; wv.x = cvtpk(acc[et][4 * i4] * rstd * __uint_as_float(gg.x << 16), acc[et][4 * i4 + 1] * rstd * __uint_as_float(gg.x & 0xffff0000u));
;                   wv.y = cvtpk(acc[et][4 * i4 + 2] * rstd * __uint_as_float(gg.y << 16), acc[et][4 * i4 + 3] * rstd * __uint_as_float(gg.y & 0xffff0000u));
;                   if (!dry || rstd == 1.2345e38f) *(v2u*)p4 = wv; if (i4 == 3 && (et & 1)) asm volatile("" ::: "memory"); } }
	v_bfi_b32 v238, v230, v90, v204
	v_bfi_b32 v239, v230, v91, v205
	v_bfi_b32 v240, v230, v92, v206
	v_bfi_b32 v241, v230, v93, v207
	v_mov_b32_dpp v242, v238 quad_perm:[1,0,3,2] row_mask:0xf bank_mask:0xf
	v_mov_b32_dpp v243, v239 quad_perm:[1,0,3,2] row_mask:0xf bank_mask:0xf
	v_mov_b32_dpp v244, v240 quad_perm:[1,0,3,2] row_mask:0xf bank_mask:0xf
	v_mov_b32_dpp v245, v241 quad_perm:[1,0,3,2] row_mask:0xf bank_mask:0xf
	v_bfi_b32 v90, v230, v242, v90
	v_bfi_b32 v91, v230, v243, v91
	v_bfi_b32 v92, v230, v244, v92
	v_bfi_b32 v93, v230, v245, v93
	v_bfi_b32 v204, v230, v204, v242
	v_bfi_b32 v205, v230, v205, v243
	v_bfi_b32 v206, v230, v206, v244
	v_bfi_b32 v207, v230, v207, v245
	v_permlane32_swap_b32_e32 v90, v92
	v_permlane32_swap_b32_e32 v91, v93
	v_permlane32_swap_b32_e32 v204, v206
	v_permlane32_swap_b32_e32 v205, v207
	v_lshlrev_b32_e32 v57, 16, v90
	v_and_b32_e32 v58, 0xffff0000, v90
	v_lshlrev_b32_e32 v59, 16, v91
	v_and_b32_e32 v60, 0xffff0000, v91
	v_mul_f32_e32 v53, v162, v52
	v_mul_f32_e32 v54, v163, v52
	v_mul_f32_e32 v55, v164, v52
	v_mul_f32_e32 v56, v165, v52
	v_mul_f32_e32 v53, v53, v57
	v_mul_f32_e32 v54, v54, v58
	v_mul_f32_e32 v55, v55, v59
	v_mul_f32_e32 v56, v56, v60
	v_cvt_pk_bf16_f32 v250, v53, v54
	v_cvt_pk_bf16_f32 v251, v55, v56
	v_lshlrev_b32_e32 v57, 16, v92
	v_and_b32_e32 v58, 0xffff0000, v92
	v_lshlrev_b32_e32 v59, 16, v93
	v_and_b32_e32 v60, 0xffff0000, v93
	v_mul_f32_e32 v53, v166, v52
	v_mul_f32_e32 v54, v167, v52
	v_mul_f32_e32 v55, v168, v52
	v_mul_f32_e32 v56, v169, v52
	v_mul_f32_e32 v53, v53, v57
	v_mul_f32_e32 v54, v54, v58
	v_mul_f32_e32 v55, v55, v59
	v_mul_f32_e32 v56, v56, v60
	v_cvt_pk_bf16_f32 v252, v53, v54
	v_cvt_pk_bf16_f32 v253, v55, v56
	v_lshlrev_b32_e32 v57, 16, v204
	v_and_b32_e32 v58, 0xffff0000, v204
	v_lshlrev_b32_e32 v59, 16, v205
	v_and_b32_e32 v60, 0xffff0000, v205
	v_mul_f32_e32 v53, v170, v52
	v_mul_f32_e32 v54, v171, v52
	v_mul_f32_e32 v55, v172, v52
	v_mul_f32_e32 v56, v173, v52
	v_mul_f32_e32 v53, v53, v57
	v_mul_f32_e32 v54, v54, v58
	v_mul_f32_e32 v55, v55, v59
	v_mul_f32_e32 v56, v56, v60
	v_cvt_pk_bf16_f32 v224, v53, v54
	v_cvt_pk_bf16_f32 v225, v55, v56
	v_lshlrev_b32_e32 v57, 16, v206
	v_and_b32_e32 v58, 0xffff0000, v206
	v_lshlrev_b32_e32 v59, 16, v207
	v_and_b32_e32 v60, 0xffff0000, v207
	v_mul_f32_e32 v53, v174, v52
	v_mul_f32_e32 v54, v175, v52
	v_mul_f32_e32 v55, v176, v52
	v_mul_f32_e32 v56, v177, v52
	v_mul_f32_e32 v53, v53, v57
	v_mul_f32_e32 v54, v54, v58
	v_mul_f32_e32 v55, v55, v59
	v_mul_f32_e32 v56, v56, v60
	v_cvt_pk_bf16_f32 v226, v53, v54
	v_cvt_pk_bf16_f32 v227, v55, v56
	s_nop 0
	v_permlane32_swap_b32_e32 v250, v252
	v_permlane32_swap_b32_e32 v251, v253
	v_permlane32_swap_b32_e32 v224, v226
	v_permlane32_swap_b32_e32 v225, v227
	v_bfi_b32 v238, v230, v250, v224
	v_bfi_b32 v239, v230, v251, v225
	v_bfi_b32 v240, v230, v252, v226
	v_bfi_b32 v241, v230, v253, v227
	v_mov_b32_dpp v242, v238 quad_perm:[1,0,3,2] row_mask:0xf bank_mask:0xf
	v_mov_b32_dpp v243, v239 quad_perm:[1,0,3,2] row_mask:0xf bank_mask:0xf
	v_mov_b32_dpp v244, v240 quad_perm:[1,0,3,2] row_mask:0xf bank_mask:0xf
	v_mov_b32_dpp v245, v241 quad_perm:[1,0,3,2] row_mask:0xf bank_mask:0xf
	v_bfi_b32 v250, v230, v242, v250
	v_bfi_b32 v251, v230, v243, v251
	v_bfi_b32 v252, v230, v244, v252
	v_bfi_b32 v253, v230, v245, v253
	v_bfi_b32 v242, v230, v224, v242
	v_bfi_b32 v243, v230, v225, v243
	v_bfi_b32 v244, v230, v226, v244
	v_bfi_b32 v245, v230, v227, v245
	global_store_dwordx4 v[50:51], v[250:253], off offset:-1984
	global_store_dwordx4 v[50:51], v[242:245], off offset:2112
	global_load_dwordx4 v[90:93], v[50:51], off offset:-1728
	global_load_dwordx4 v[204:207], v[50:51], off offset:2368
	s_waitcnt vmcnt(10)
	v_bfi_b32 v238, v230, v208, v212
	v_bfi_b32 v239, v230, v209, v213
	v_bfi_b32 v240, v230, v210, v214
	v_bfi_b32 v241, v230, v211, v215
	v_mov_b32_dpp v242, v238 quad_perm:[1,0,3,2] row_mask:0xf bank_mask:0xf
	v_mov_b32_dpp v243, v239 quad_perm:[1,0,3,2] row_mask:0xf bank_mask:0xf
	v_mov_b32_dpp v244, v240 quad_perm:[1,0,3,2] row_mask:0xf bank_mask:0xf
	v_mov_b32_dpp v245, v241 quad_perm:[1,0,3,2] row_mask:0xf bank_mask:0xf
	v_bfi_b32 v208, v230, v242, v208
	v_bfi_b32 v209, v230, v243, v209
	v_bfi_b32 v210, v230, v244, v210
	v_bfi_b32 v211, v230, v245, v211
	v_bfi_b32 v212, v230, v212, v242
	v_bfi_b32 v213, v230, v213, v243
	v_bfi_b32 v214, v230, v214, v244
	v_bfi_b32 v215, v230, v215, v245
	v_permlane32_swap_b32_e32 v208, v210
	v_permlane32_swap_b32_e32 v209, v211
	v_permlane32_swap_b32_e32 v212, v214
	v_permlane32_swap_b32_e32 v213, v215
	v_lshlrev_b32_e32 v57, 16, v208
	v_and_b32_e32 v58, 0xffff0000, v208
	v_lshlrev_b32_e32 v59, 16, v209
	v_and_b32_e32 v60, 0xffff0000, v209
	v_mul_f32_e32 v53, v146, v52
	v_mul_f32_e32 v54, v147, v52
	v_mul_f32_e32 v55, v148, v52
	v_mul_f32_e32 v56, v149, v52
	v_mul_f32_e32 v53, v53, v57
	v_mul_f32_e32 v54, v54, v58
	v_mul_f32_e32 v55, v55, v59
	v_mul_f32_e32 v56, v56, v60
	v_cvt_pk_bf16_f32 v250, v53, v54
	v_cvt_pk_bf16_f32 v251, v55, v56
	v_lshlrev_b32_e32 v57, 16, v210
	v_and_b32_e32 v58, 0xffff0000, v210
	v_lshlrev_b32_e32 v59, 16, v211
	v_and_b32_e32 v60, 0xffff0000, v211
	v_mul_f32_e32 v53, v150, v52
	v_mul_f32_e32 v54, v151, v52
	v_mul_f32_e32 v55, v152, v52
	v_mul_f32_e32 v56, v153, v52
	v_mul_f32_e32 v53, v53, v57
	v_mul_f32_e32 v54, v54, v58
	v_mul_f32_e32 v55, v55, v59
	v_mul_f32_e32 v56, v56, v60
	v_cvt_pk_bf16_f32 v252, v53, v54
	v_cvt_pk_bf16_f32 v253, v55, v56
	v_lshlrev_b32_e32 v57, 16, v212
	v_and_b32_e32 v58, 0xffff0000, v212
	v_lshlrev_b32_e32 v59, 16, v213
	v_and_b32_e32 v60, 0xffff0000, v213
	v_mul_f32_e32 v53, v154, v52
; __device__ __forceinline__ unsigned cvtpk(float lo, float hi) { return pg8::cvt_pk_bf16(lo, hi); }
;     ...
;         { R2_IDS const float rstd = 1.0f / sqrtf((ssp[32 * nt + r] + ssp[128 + 32 * nt + r]) * (1.0f / 512.0f) + RMS_EPS);
;           bf16* gp = GY + ((size_t)((bh >> 2) * SEQ + tq0 + 32 * nt + r)) * 2048 + h * 512 + 256 * eh + 4 * hh;
; #pragma unroll
;           for (int et = 0; et < 8; ++et)
; #pragma unroll
;               for (int i4 = 0; i4 < 4; ++i4) { bf16* p4 = gp + 32 * et + 8 * i4; const v2u gg = *(const v2u*)p4;
;                   v2u wv; wv.x = cvtpk(acc[et][4 * i4] * rstd * __uint_as_float(gg.x << 16), acc[et][4 * i4 + 1] * rstd * __uint_as_float(gg.x & 0xffff0000u));
;                   wv.y = cvtpk(acc[et][4 * i4 + 2] * rstd * __uint_as_float(gg.y << 16), acc[et][4 * i4 + 3] * rstd * __uint_as_float(gg.y & 0xffff0000u));
;                   if (!dry || rstd == 1.2345e38f) *(v2u*)p4 = wv; if (i4 == 3 && (et & 1)) asm volatile("" ::: "memory"); } }
	v_mul_f32_e32 v54, v155, v52
	v_mul_f32_e32 v55, v156, v52
	v_mul_f32_e32 v56, v157, v52
	v_mul_f32_e32 v53, v53, v57
	v_mul_f32_e32 v54, v54, v58
	v_mul_f32_e32 v55, v55, v59
	v_mul_f32_e32 v56, v56, v60
	v_cvt_pk_bf16_f32 v224, v53, v54
	v_cvt_pk_bf16_f32 v225, v55, v56
	v_lshlrev_b32_e32 v57, 16, v214
	v_and_b32_e32 v58, 0xffff0000, v214
	v_lshlrev_b32_e32 v59, 16, v215
	v_and_b32_e32 v60, 0xffff0000, v215
	v_mul_f32_e32 v53, v158, v52
	v_mul_f32_e32 v54, v159, v52
	v_mul_f32_e32 v55, v160, v52
	v_mul_f32_e32 v56, v161, v52
	v_mul_f32_e32 v53, v53, v57
	v_mul_f32_e32 v54, v54, v58
	v_mul_f32_e32 v55, v55, v59
	v_mul_f32_e32 v56, v56, v60
	v_cvt_pk_bf16_f32 v226, v53, v54
	v_cvt_pk_bf16_f32 v227, v55, v56
	s_nop 0
	v_permlane32_swap_b32_e32 v250, v252
	v_permlane32_swap_b32_e32 v251, v253
	v_permlane32_swap_b32_e32 v224, v226
	v_permlane32_swap_b32_e32 v225, v227
	v_bfi_b32 v238, v230, v250, v224
	v_bfi_b32 v239, v230, v251, v225
	v_bfi_b32 v240, v230, v252, v226
	v_bfi_b32 v241, v230, v253, v227
	v_mov_b32_dpp v242, v238 quad_perm:[1,0,3,2] row_mask:0xf bank_mask:0xf
	v_mov_b32_dpp v243, v239 quad_perm:[1,0,3,2] row_mask:0xf bank_mask:0xf
	v_mov_b32_dpp v244, v240 quad_perm:[1,0,3,2] row_mask:0xf bank_mask:0xf
	v_mov_b32_dpp v245, v241 quad_perm:[1,0,3,2] row_mask:0xf bank_mask:0xf
	v_bfi_b32 v250, v230, v242, v250
	v_bfi_b32 v251, v230, v243, v251
	v_bfi_b32 v252, v230, v244, v252
	v_bfi_b32 v253, v230, v245, v253
	v_bfi_b32 v242, v230, v224, v242
	v_bfi_b32 v243, v230, v225, v243
	v_bfi_b32 v244, v230, v226, v244
	v_bfi_b32 v245, v230, v227, v245
	global_store_dwordx4 v[50:51], v[250:253], off offset:-1920
	global_store_dwordx4 v[50:51], v[242:245], off offset:2176
	global_load_dwordx4 v[208:211], v[50:51], off offset:-1664
	global_load_dwordx4 v[212:215], v[50:51], off offset:2432
	s_waitcnt vmcnt(12)
	v_bfi_b32 v238, v230, v216, v220
	v_bfi_b32 v239, v230, v217, v221
	v_bfi_b32 v240, v230, v218, v222
	v_bfi_b32 v241, v230, v219, v223
	v_mov_b32_dpp v242, v238 quad_perm:[1,0,3,2] row_mask:0xf bank_mask:0xf
	v_mov_b32_dpp v243, v239 quad_perm:[1,0,3,2] row_mask:0xf bank_mask:0xf
	v_mov_b32_dpp v244, v240 quad_perm:[1,0,3,2] row_mask:0xf bank_mask:0xf
	v_mov_b32_dpp v245, v241 quad_perm:[1,0,3,2] row_mask:0xf bank_mask:0xf
	v_bfi_b32 v216, v230, v242, v216
	v_bfi_b32 v217, v230, v243, v217
	v_bfi_b32 v218, v230, v244, v218
	v_bfi_b32 v219, v230, v245, v219
	v_bfi_b32 v220, v230, v220, v242
	v_bfi_b32 v221, v230, v221, v243
	v_bfi_b32 v222, v230, v222, v244
	v_bfi_b32 v223, v230, v223, v245
	v_permlane32_swap_b32_e32 v216, v218
	v_permlane32_swap_b32_e32 v217, v219
	v_permlane32_swap_b32_e32 v220, v222
	v_permlane32_swap_b32_e32 v221, v223
	v_lshlrev_b32_e32 v57, 16, v216
	v_and_b32_e32 v58, 0xffff0000, v216
	v_lshlrev_b32_e32 v59, 16, v217
	v_and_b32_e32 v60, 0xffff0000, v217
	v_mul_f32_e32 v53, v130, v52
	v_mul_f32_e32 v54, v131, v52
	v_mul_f32_e32 v55, v132, v52
	v_mul_f32_e32 v56, v133, v52
	v_mul_f32_e32 v53, v53, v57
	v_mul_f32_e32 v54, v54, v58
	v_mul_f32_e32 v55, v55, v59
	v_mul_f32_e32 v56, v56, v60
	v_cvt_pk_bf16_f32 v250, v53, v54
	v_cvt_pk_bf16_f32 v251, v55, v56
	v_lshlrev_b32_e32 v57, 16, v218
	v_and_b32_e32 v58, 0xffff0000, v218
	v_lshlrev_b32_e32 v59, 16, v219
	v_and_b32_e32 v60, 0xffff0000, v219
	v_mul_f32_e32 v53, v134, v52
	v_mul_f32_e32 v54, v135, v52
	v_mul_f32_e32 v55, v136, v52
	v_mul_f32_e32 v56, v137, v52
	v_mul_f32_e32 v53, v53, v57
	v_mul_f32_e32 v54, v54, v58
	v_mul_f32_e32 v55, v55, v59
	v_mul_f32_e32 v56, v56, v60
	v_cvt_pk_bf16_f32 v252, v53, v54
	v_cvt_pk_bf16_f32 v253, v55, v56
	v_lshlrev_b32_e32 v57, 16, v220
	v_and_b32_e32 v58, 0xffff0000, v220
	v_lshlrev_b32_e32 v59, 16, v221
	v_and_b32_e32 v60, 0xffff0000, v221
	v_mul_f32_e32 v53, v138, v52
	v_mul_f32_e32 v54, v139, v52
	v_mul_f32_e32 v55, v140, v52
	v_mul_f32_e32 v56, v141, v52
	v_mul_f32_e32 v53, v53, v57
	v_mul_f32_e32 v54, v54, v58
	v_mul_f32_e32 v55, v55, v59
	v_mul_f32_e32 v56, v56, v60
	v_cvt_pk_bf16_f32 v224, v53, v54
	v_cvt_pk_bf16_f32 v225, v55, v56
	v_lshlrev_b32_e32 v57, 16, v222
	v_and_b32_e32 v58, 0xffff0000, v222
	v_lshlrev_b32_e32 v59, 16, v223
	v_and_b32_e32 v60, 0xffff0000, v223
	v_mul_f32_e32 v53, v142, v52
	v_mul_f32_e32 v54, v143, v52
	v_mul_f32_e32 v55, v144, v52
	v_mul_f32_e32 v56, v145, v52
	v_mul_f32_e32 v53, v53, v57
	v_mul_f32_e32 v54, v54, v58
	v_mul_f32_e32 v55, v55, v59
	v_mul_f32_e32 v56, v56, v60
	v_cvt_pk_bf16_f32 v226, v53, v54
	v_cvt_pk_bf16_f32 v227, v55, v56
	s_nop 0
	v_permlane32_swap_b32_e32 v250, v252
	v_permlane32_swap_b32_e32 v251, v253
	v_permlane32_swap_b32_e32 v224, v226
	v_permlane32_swap_b32_e32 v225, v227
	v_bfi_b32 v238, v230, v250, v224
	v_bfi_b32 v239, v230, v251, v225
	v_bfi_b32 v240, v230, v252, v226
	v_bfi_b32 v241, v230, v253, v227
	v_mov_b32_dpp v242, v238 quad_perm:[1,0,3,2] row_mask:0xf bank_mask:0xf
	v_mov_b32_dpp v243, v239 quad_perm:[1,0,3,2] row_mask:0xf bank_mask:0xf
	v_mov_b32_dpp v244, v240 quad_perm:[1,0,3,2] row_mask:0xf bank_mask:0xf
	v_mov_b32_dpp v245, v241 quad_perm:[1,0,3,2] row_mask:0xf bank_mask:0xf
	v_bfi_b32 v250, v230, v242, v250
	v_bfi_b32 v251, v230, v243, v251
	v_bfi_b32 v252, v230, v244, v252
	v_bfi_b32 v253, v230, v245, v253
	v_bfi_b32 v242, v230, v224, v242
	v_bfi_b32 v243, v230, v225, v243
	v_bfi_b32 v244, v230, v226, v244
	v_bfi_b32 v245, v230, v227, v245
	global_store_dwordx4 v[50:51], v[250:253], off offset:-1856
	global_store_dwordx4 v[50:51], v[242:245], off offset:2240
	global_load_dwordx4 v[216:219], v[50:51], off offset:-1600
	global_load_dwordx4 v[220:223], v[50:51], off offset:2496
	s_waitcnt vmcnt(12)
; __device__ __forceinline__ unsigned cvtpk(float lo, float hi) { return pg8::cvt_pk_bf16(lo, hi); }
;     ...
;         { R2_IDS const float rstd = 1.0f / sqrtf((ssp[32 * nt + r] + ssp[128 + 32 * nt + r]) * (1.0f / 512.0f) + RMS_EPS);
;           bf16* gp = GY + ((size_t)((bh >> 2) * SEQ + tq0 + 32 * nt + r)) * 2048 + h * 512 + 256 * eh + 4 * hh;
; #pragma unroll
;           for (int et = 0; et < 8; ++et)
; #pragma unroll
;               for (int i4 = 0; i4 < 4; ++i4) { bf16* p4 = gp + 32 * et + 8 * i4; const v2u gg = *(const v2u*)p4;
;                   v2u wv; wv.x = cvtpk(acc[et][4 * i4] * rstd * __uint_as_float(gg.x << 16), acc[et][4 * i4 + 1] * rstd * __uint_as_float(gg.x & 0xffff0000u));
;                   wv.y = cvtpk(acc[et][4 * i4 + 2] * rstd * __uint_as_float(gg.y << 16), acc[et][4 * i4 + 3] * rstd * __uint_as_float(gg.y & 0xffff0000u));
;                   if (!dry || rstd == 1.2345e38f) *(v2u*)p4 = wv; if (i4 == 3 && (et & 1)) asm volatile("" ::: "memory"); } }
	v_bfi_b32 v238, v230, v82, v86
	v_bfi_b32 v239, v230, v83, v87
	v_bfi_b32 v240, v230, v84, v88
	v_bfi_b32 v241, v230, v85, v89
	v_mov_b32_dpp v242, v238 quad_perm:[1,0,3,2] row_mask:0xf bank_mask:0xf
	v_mov_b32_dpp v243, v239 quad_perm:[1,0,3,2] row_mask:0xf bank_mask:0xf
	v_mov_b32_dpp v244, v240 quad_perm:[1,0,3,2] row_mask:0xf bank_mask:0xf
	v_mov_b32_dpp v245, v241 quad_perm:[1,0,3,2] row_mask:0xf bank_mask:0xf
	v_bfi_b32 v82, v230, v242, v82
	v_bfi_b32 v83, v230, v243, v83
	v_bfi_b32 v84, v230, v244, v84
	v_bfi_b32 v85, v230, v245, v85
	v_bfi_b32 v86, v230, v86, v242
	v_bfi_b32 v87, v230, v87, v243
	v_bfi_b32 v88, v230, v88, v244
	v_bfi_b32 v89, v230, v89, v245
	v_permlane32_swap_b32_e32 v82, v84
	v_permlane32_swap_b32_e32 v83, v85
	v_permlane32_swap_b32_e32 v86, v88
	v_permlane32_swap_b32_e32 v87, v89
	v_lshlrev_b32_e32 v57, 16, v82
	v_and_b32_e32 v58, 0xffff0000, v82
	v_lshlrev_b32_e32 v59, 16, v83
	v_and_b32_e32 v60, 0xffff0000, v83
	v_mul_f32_e32 v53, v66, v52
	v_mul_f32_e32 v54, v67, v52
	v_mul_f32_e32 v55, v68, v52
	v_mul_f32_e32 v56, v69, v52
	v_mul_f32_e32 v53, v53, v57
	v_mul_f32_e32 v54, v54, v58
	v_mul_f32_e32 v55, v55, v59
	v_mul_f32_e32 v56, v56, v60
	v_cvt_pk_bf16_f32 v250, v53, v54
	v_cvt_pk_bf16_f32 v251, v55, v56
	v_lshlrev_b32_e32 v57, 16, v84
	v_and_b32_e32 v58, 0xffff0000, v84
	v_lshlrev_b32_e32 v59, 16, v85
	v_and_b32_e32 v60, 0xffff0000, v85
	v_mul_f32_e32 v53, v70, v52
	v_mul_f32_e32 v54, v71, v52
	v_mul_f32_e32 v55, v72, v52
	v_mul_f32_e32 v56, v73, v52
	v_mul_f32_e32 v53, v53, v57
	v_mul_f32_e32 v54, v54, v58
	v_mul_f32_e32 v55, v55, v59
	v_mul_f32_e32 v56, v56, v60
	v_cvt_pk_bf16_f32 v252, v53, v54
	v_cvt_pk_bf16_f32 v253, v55, v56
	v_lshlrev_b32_e32 v57, 16, v86
	v_and_b32_e32 v58, 0xffff0000, v86
	v_lshlrev_b32_e32 v59, 16, v87
	v_and_b32_e32 v60, 0xffff0000, v87
	v_mul_f32_e32 v53, v74, v52
	v_mul_f32_e32 v54, v75, v52
	v_mul_f32_e32 v55, v76, v52
	v_mul_f32_e32 v56, v77, v52
	v_mul_f32_e32 v53, v53, v57
	v_mul_f32_e32 v54, v54, v58
	v_mul_f32_e32 v55, v55, v59
	v_mul_f32_e32 v56, v56, v60
	v_cvt_pk_bf16_f32 v224, v53, v54
	v_cvt_pk_bf16_f32 v225, v55, v56
	v_lshlrev_b32_e32 v57, 16, v88
	v_and_b32_e32 v58, 0xffff0000, v88
	v_lshlrev_b32_e32 v59, 16, v89
	v_and_b32_e32 v60, 0xffff0000, v89
	v_mul_f32_e32 v53, v78, v52
	v_mul_f32_e32 v54, v79, v52
	v_mul_f32_e32 v55, v80, v52
	v_mul_f32_e32 v56, v81, v52
	v_mul_f32_e32 v53, v53, v57
	v_mul_f32_e32 v54, v54, v58
	v_mul_f32_e32 v55, v55, v59
	v_mul_f32_e32 v56, v56, v60
	v_cvt_pk_bf16_f32 v226, v53, v54
	v_cvt_pk_bf16_f32 v227, v55, v56
	s_nop 0
	v_permlane32_swap_b32_e32 v250, v252
	v_permlane32_swap_b32_e32 v251, v253
	v_permlane32_swap_b32_e32 v224, v226
	v_permlane32_swap_b32_e32 v225, v227
	v_bfi_b32 v238, v230, v250, v224
	v_bfi_b32 v239, v230, v251, v225
	v_bfi_b32 v240, v230, v252, v226
	v_bfi_b32 v241, v230, v253, v227
	v_mov_b32_dpp v242, v238 quad_perm:[1,0,3,2] row_mask:0xf bank_mask:0xf
	v_mov_b32_dpp v243, v239 quad_perm:[1,0,3,2] row_mask:0xf bank_mask:0xf
	v_mov_b32_dpp v244, v240 quad_perm:[1,0,3,2] row_mask:0xf bank_mask:0xf
	v_mov_b32_dpp v245, v241 quad_perm:[1,0,3,2] row_mask:0xf bank_mask:0xf
	v_bfi_b32 v250, v230, v242, v250
	v_bfi_b32 v251, v230, v243, v251
	v_bfi_b32 v252, v230, v244, v252
	v_bfi_b32 v253, v230, v245, v253
	v_bfi_b32 v242, v230, v224, v242
	v_bfi_b32 v243, v230, v225, v243
	v_bfi_b32 v244, v230, v226, v244
	v_bfi_b32 v245, v230, v227, v245
	global_store_dwordx4 v[50:51], v[250:253], off offset:-1792
	global_store_dwordx4 v[50:51], v[242:245], off offset:2304
	s_waitcnt vmcnt(10)
	v_bfi_b32 v238, v230, v90, v204
	v_bfi_b32 v239, v230, v91, v205
	v_bfi_b32 v240, v230, v92, v206
	v_bfi_b32 v241, v230, v93, v207
	v_mov_b32_dpp v242, v238 quad_perm:[1,0,3,2] row_mask:0xf bank_mask:0xf
	v_mov_b32_dpp v243, v239 quad_perm:[1,0,3,2] row_mask:0xf bank_mask:0xf
	v_mov_b32_dpp v244, v240 quad_perm:[1,0,3,2] row_mask:0xf bank_mask:0xf
	v_mov_b32_dpp v245, v241 quad_perm:[1,0,3,2] row_mask:0xf bank_mask:0xf
	v_bfi_b32 v90, v230, v242, v90
	v_bfi_b32 v91, v230, v243, v91
	v_bfi_b32 v92, v230, v244, v92
	v_bfi_b32 v93, v230, v245, v93
	v_bfi_b32 v204, v230, v204, v242
	v_bfi_b32 v205, v230, v205, v243
	v_bfi_b32 v206, v230, v206, v244
	v_bfi_b32 v207, v230, v207, v245
	v_permlane32_swap_b32_e32 v90, v92
	v_permlane32_swap_b32_e32 v91, v93
	v_permlane32_swap_b32_e32 v204, v206
	v_permlane32_swap_b32_e32 v205, v207
	v_lshlrev_b32_e32 v57, 16, v90
	v_and_b32_e32 v58, 0xffff0000, v90
	v_lshlrev_b32_e32 v59, 16, v91
	v_and_b32_e32 v60, 0xffff0000, v91
	v_mul_f32_e32 v53, v34, v52
	v_mul_f32_e32 v54, v35, v52
	v_mul_f32_e32 v55, v36, v52
	v_mul_f32_e32 v56, v37, v52
	v_mul_f32_e32 v53, v53, v57
	v_mul_f32_e32 v54, v54, v58
	v_mul_f32_e32 v55, v55, v59
	v_mul_f32_e32 v56, v56, v60
	v_cvt_pk_bf16_f32 v250, v53, v54
	v_cvt_pk_bf16_f32 v251, v55, v56
	v_lshlrev_b32_e32 v57, 16, v92
	v_and_b32_e32 v58, 0xffff0000, v92
	v_lshlrev_b32_e32 v59, 16, v93
	v_and_b32_e32 v60, 0xffff0000, v93
	v_mul_f32_e32 v53, v38, v52
	v_mul_f32_e32 v54, v39, v52
	v_mul_f32_e32 v55, v40, v52
	v_mul_f32_e32 v56, v41, v52
	v_mul_f32_e32 v53, v53, v57
	v_mul_f32_e32 v54, v54, v58
	v_mul_f32_e32 v55, v55, v59
	v_mul_f32_e32 v56, v56, v60
	v_cvt_pk_bf16_f32 v252, v53, v54
	v_cvt_pk_bf16_f32 v253, v55, v56
	v_lshlrev_b32_e32 v57, 16, v204
	v_and_b32_e32 v58, 0xffff0000, v204
	v_lshlrev_b32_e32 v59, 16, v205
	v_and_b32_e32 v60, 0xffff0000, v205
	v_mul_f32_e32 v53, v42, v52
	v_mul_f32_e32 v54, v43, v52
	v_mul_f32_e32 v55, v44, v52
	v_mul_f32_e32 v56, v45, v52
	v_mul_f32_e32 v53, v53, v57
	v_mul_f32_e32 v54, v54, v58
	v_mul_f32_e32 v55, v55, v59
	v_mul_f32_e32 v56, v56, v60
; __device__ __forceinline__ unsigned cvtpk(float lo, float hi) { return pg8::cvt_pk_bf16(lo, hi); }
;     ...
;         { R2_IDS const float rstd = 1.0f / sqrtf((ssp[32 * nt + r] + ssp[128 + 32 * nt + r]) * (1.0f / 512.0f) + RMS_EPS);
;           bf16* gp = GY + ((size_t)((bh >> 2) * SEQ + tq0 + 32 * nt + r)) * 2048 + h * 512 + 256 * eh + 4 * hh;
; #pragma unroll
;           for (int et = 0; et < 8; ++et)
; #pragma unroll
;               for (int i4 = 0; i4 < 4; ++i4) { bf16* p4 = gp + 32 * et + 8 * i4; const v2u gg = *(const v2u*)p4;
;                   v2u wv; wv.x = cvtpk(acc[et][4 * i4] * rstd * __uint_as_float(gg.x << 16), acc[et][4 * i4 + 1] * rstd * __uint_as_float(gg.x & 0xffff0000u));
;                   wv.y = cvtpk(acc[et][4 * i4 + 2] * rstd * __uint_as_float(gg.y << 16), acc[et][4 * i4 + 3] * rstd * __uint_as_float(gg.y & 0xffff0000u));
;                   if (!dry || rstd == 1.2345e38f) *(v2u*)p4 = wv; if (i4 == 3 && (et & 1)) asm volatile("" ::: "memory"); } }
	v_cvt_pk_bf16_f32 v224, v53, v54
	v_cvt_pk_bf16_f32 v225, v55, v56
	v_lshlrev_b32_e32 v57, 16, v206
	v_and_b32_e32 v58, 0xffff0000, v206
	v_lshlrev_b32_e32 v59, 16, v207
	v_and_b32_e32 v60, 0xffff0000, v207
	v_mul_f32_e32 v53, v46, v52
	v_mul_f32_e32 v54, v47, v52
	v_mul_f32_e32 v55, v48, v52
	v_mul_f32_e32 v56, v49, v52
	v_mul_f32_e32 v53, v53, v57
	v_mul_f32_e32 v54, v54, v58
	v_mul_f32_e32 v55, v55, v59
	v_mul_f32_e32 v56, v56, v60
	v_cvt_pk_bf16_f32 v226, v53, v54
	v_cvt_pk_bf16_f32 v227, v55, v56
	s_nop 0
	v_permlane32_swap_b32_e32 v250, v252
	v_permlane32_swap_b32_e32 v251, v253
	v_permlane32_swap_b32_e32 v224, v226
	v_permlane32_swap_b32_e32 v225, v227
	v_bfi_b32 v238, v230, v250, v224
	v_bfi_b32 v239, v230, v251, v225
	v_bfi_b32 v240, v230, v252, v226
	v_bfi_b32 v241, v230, v253, v227
	v_mov_b32_dpp v242, v238 quad_perm:[1,0,3,2] row_mask:0xf bank_mask:0xf
	v_mov_b32_dpp v243, v239 quad_perm:[1,0,3,2] row_mask:0xf bank_mask:0xf
	v_mov_b32_dpp v244, v240 quad_perm:[1,0,3,2] row_mask:0xf bank_mask:0xf
	v_mov_b32_dpp v245, v241 quad_perm:[1,0,3,2] row_mask:0xf bank_mask:0xf
	v_bfi_b32 v250, v230, v242, v250
	v_bfi_b32 v251, v230, v243, v251
	v_bfi_b32 v252, v230, v244, v252
	v_bfi_b32 v253, v230, v245, v253
	v_bfi_b32 v242, v230, v224, v242
	v_bfi_b32 v243, v230, v225, v243
	v_bfi_b32 v244, v230, v226, v244
	v_bfi_b32 v245, v230, v227, v245
	global_store_dwordx4 v[50:51], v[250:253], off offset:-1728
	global_store_dwordx4 v[50:51], v[242:245], off offset:2368
	s_waitcnt vmcnt(8)
	v_bfi_b32 v238, v230, v208, v212
	v_bfi_b32 v239, v230, v209, v213
	v_bfi_b32 v240, v230, v210, v214
	v_bfi_b32 v241, v230, v211, v215
	v_mov_b32_dpp v242, v238 quad_perm:[1,0,3,2] row_mask:0xf bank_mask:0xf
	v_mov_b32_dpp v243, v239 quad_perm:[1,0,3,2] row_mask:0xf bank_mask:0xf
	v_mov_b32_dpp v244, v240 quad_perm:[1,0,3,2] row_mask:0xf bank_mask:0xf
	v_mov_b32_dpp v245, v241 quad_perm:[1,0,3,2] row_mask:0xf bank_mask:0xf
	v_bfi_b32 v208, v230, v242, v208
	v_bfi_b32 v209, v230, v243, v209
	v_bfi_b32 v210, v230, v244, v210
	v_bfi_b32 v211, v230, v245, v211
	v_bfi_b32 v212, v230, v212, v242
	v_bfi_b32 v213, v230, v213, v243
	v_bfi_b32 v214, v230, v214, v244
	v_bfi_b32 v215, v230, v215, v245
	v_permlane32_swap_b32_e32 v208, v210
	v_permlane32_swap_b32_e32 v209, v211
	v_permlane32_swap_b32_e32 v212, v214
	v_permlane32_swap_b32_e32 v213, v215
	v_lshlrev_b32_e32 v57, 16, v208
	v_and_b32_e32 v58, 0xffff0000, v208
	v_lshlrev_b32_e32 v59, 16, v209
	v_and_b32_e32 v60, 0xffff0000, v209
	v_mul_f32_e32 v53, v16, v52
	v_mul_f32_e32 v54, v17, v52
	v_mul_f32_e32 v55, v18, v52
	v_mul_f32_e32 v56, v19, v52
	v_mul_f32_e32 v53, v53, v57
	v_mul_f32_e32 v54, v54, v58
	v_mul_f32_e32 v55, v55, v59
	v_mul_f32_e32 v56, v56, v60
	v_cvt_pk_bf16_f32 v250, v53, v54
	v_cvt_pk_bf16_f32 v251, v55, v56
	v_lshlrev_b32_e32 v57, 16, v210
	v_and_b32_e32 v58, 0xffff0000, v210
	v_lshlrev_b32_e32 v59, 16, v211
	v_and_b32_e32 v60, 0xffff0000, v211
	v_mul_f32_e32 v53, v20, v52
	v_mul_f32_e32 v54, v21, v52
	v_mul_f32_e32 v55, v22, v52
	v_mul_f32_e32 v56, v23, v52
	v_mul_f32_e32 v53, v53, v57
	v_mul_f32_e32 v54, v54, v58
	v_mul_f32_e32 v55, v55, v59
	v_mul_f32_e32 v56, v56, v60
	v_cvt_pk_bf16_f32 v252, v53, v54
	v_cvt_pk_bf16_f32 v253, v55, v56
	v_lshlrev_b32_e32 v57, 16, v212
	v_and_b32_e32 v58, 0xffff0000, v212
	v_lshlrev_b32_e32 v59, 16, v213
	v_and_b32_e32 v60, 0xffff0000, v213
	v_mul_f32_e32 v53, v24, v52
	v_mul_f32_e32 v54, v25, v52
	v_mul_f32_e32 v55, v26, v52
	v_mul_f32_e32 v56, v27, v52
	v_mul_f32_e32 v53, v53, v57
	v_mul_f32_e32 v54, v54, v58
	v_mul_f32_e32 v55, v55, v59
	v_mul_f32_e32 v56, v56, v60
	v_cvt_pk_bf16_f32 v224, v53, v54
	v_cvt_pk_bf16_f32 v225, v55, v56
	v_lshlrev_b32_e32 v57, 16, v214
	v_and_b32_e32 v58, 0xffff0000, v214
	v_lshlrev_b32_e32 v59, 16, v215
	v_and_b32_e32 v60, 0xffff0000, v215
	v_mul_f32_e32 v53, v28, v52
	v_mul_f32_e32 v54, v29, v52
	v_mul_f32_e32 v55, v30, v52
	v_mul_f32_e32 v56, v31, v52
	v_mul_f32_e32 v53, v53, v57
	v_mul_f32_e32 v54, v54, v58
	v_mul_f32_e32 v55, v55, v59
	v_mul_f32_e32 v56, v56, v60
	v_cvt_pk_bf16_f32 v226, v53, v54
	v_cvt_pk_bf16_f32 v227, v55, v56
	s_nop 0
	v_permlane32_swap_b32_e32 v250, v252
	v_permlane32_swap_b32_e32 v251, v253
	v_permlane32_swap_b32_e32 v224, v226
	v_permlane32_swap_b32_e32 v225, v227
	v_bfi_b32 v238, v230, v250, v224
	v_bfi_b32 v239, v230, v251, v225
	v_bfi_b32 v240, v230, v252, v226
	v_bfi_b32 v241, v230, v253, v227
	v_mov_b32_dpp v242, v238 quad_perm:[1,0,3,2] row_mask:0xf bank_mask:0xf
	v_mov_b32_dpp v243, v239 quad_perm:[1,0,3,2] row_mask:0xf bank_mask:0xf
	v_mov_b32_dpp v244, v240 quad_perm:[1,0,3,2] row_mask:0xf bank_mask:0xf
	v_mov_b32_dpp v245, v241 quad_perm:[1,0,3,2] row_mask:0xf bank_mask:0xf
	v_bfi_b32 v250, v230, v242, v250
	v_bfi_b32 v251, v230, v243, v251
	v_bfi_b32 v252, v230, v244, v252
	v_bfi_b32 v253, v230, v245, v253
	v_bfi_b32 v242, v230, v224, v242
	v_bfi_b32 v243, v230, v225, v243
	v_bfi_b32 v244, v230, v226, v244
	v_bfi_b32 v245, v230, v227, v245
	global_store_dwordx4 v[50:51], v[250:253], off offset:-1664
	global_store_dwordx4 v[50:51], v[242:245], off offset:2432
	s_waitcnt vmcnt(6)
; __device__ __forceinline__ unsigned cvtpk(float lo, float hi) { return pg8::cvt_pk_bf16(lo, hi); }
;     ...
;         { R2_IDS const float rstd = 1.0f / sqrtf((ssp[32 * nt + r] + ssp[128 + 32 * nt + r]) * (1.0f / 512.0f) + RMS_EPS);
;           bf16* gp = GY + ((size_t)((bh >> 2) * SEQ + tq0 + 32 * nt + r)) * 2048 + h * 512 + 256 * eh + 4 * hh;
; #pragma unroll
;           for (int et = 0; et < 8; ++et)
; #pragma unroll
;               for (int i4 = 0; i4 < 4; ++i4) { bf16* p4 = gp + 32 * et + 8 * i4; const v2u gg = *(const v2u*)p4;
;                   v2u wv; wv.x = cvtpk(acc[et][4 * i4] * rstd * __uint_as_float(gg.x << 16), acc[et][4 * i4 + 1] * rstd * __uint_as_float(gg.x & 0xffff0000u));
;                   wv.y = cvtpk(acc[et][4 * i4 + 2] * rstd * __uint_as_float(gg.y << 16), acc[et][4 * i4 + 3] * rstd * __uint_as_float(gg.y & 0xffff0000u));
;                   if (!dry || rstd == 1.2345e38f) *(v2u*)p4 = wv; if (i4 == 3 && (et & 1)) asm volatile("" ::: "memory"); } }
	v_bfi_b32 v238, v230, v216, v220
	v_bfi_b32 v239, v230, v217, v221
	v_bfi_b32 v240, v230, v218, v222
	v_bfi_b32 v241, v230, v219, v223
	v_mov_b32_dpp v242, v238 quad_perm:[1,0,3,2] row_mask:0xf bank_mask:0xf
	v_mov_b32_dpp v243, v239 quad_perm:[1,0,3,2] row_mask:0xf bank_mask:0xf
	v_mov_b32_dpp v244, v240 quad_perm:[1,0,3,2] row_mask:0xf bank_mask:0xf
	v_mov_b32_dpp v245, v241 quad_perm:[1,0,3,2] row_mask:0xf bank_mask:0xf
	v_bfi_b32 v216, v230, v242, v216
	v_bfi_b32 v217, v230, v243, v217
	v_bfi_b32 v218, v230, v244, v218
	v_bfi_b32 v219, v230, v245, v219
	v_bfi_b32 v220, v230, v220, v242
	v_bfi_b32 v221, v230, v221, v243
	v_bfi_b32 v222, v230, v222, v244
	v_bfi_b32 v223, v230, v223, v245
	v_permlane32_swap_b32_e32 v216, v218
	v_permlane32_swap_b32_e32 v217, v219
	v_permlane32_swap_b32_e32 v220, v222
	v_permlane32_swap_b32_e32 v221, v223
	v_lshlrev_b32_e32 v57, 16, v216
	v_and_b32_e32 v58, 0xffff0000, v216
	v_lshlrev_b32_e32 v59, 16, v217
	v_and_b32_e32 v60, 0xffff0000, v217
	v_mul_f32_e32 v53, v0, v52
	v_mul_f32_e32 v54, v1, v52
	v_mul_f32_e32 v55, v2, v52
	v_mul_f32_e32 v56, v3, v52
	v_mul_f32_e32 v53, v53, v57
	v_mul_f32_e32 v54, v54, v58
	v_mul_f32_e32 v55, v55, v59
	v_mul_f32_e32 v56, v56, v60
	v_cvt_pk_bf16_f32 v250, v53, v54
	v_cvt_pk_bf16_f32 v251, v55, v56
	v_lshlrev_b32_e32 v57, 16, v218
	v_and_b32_e32 v58, 0xffff0000, v218
	v_lshlrev_b32_e32 v59, 16, v219
	v_and_b32_e32 v60, 0xffff0000, v219
	v_mul_f32_e32 v53, v4, v52
	v_mul_f32_e32 v54, v5, v52
	v_mul_f32_e32 v55, v6, v52
	v_mul_f32_e32 v56, v7, v52
	v_mul_f32_e32 v53, v53, v57
	v_mul_f32_e32 v54, v54, v58
	v_mul_f32_e32 v55, v55, v59
	v_mul_f32_e32 v56, v56, v60
	v_cvt_pk_bf16_f32 v252, v53, v54
	v_cvt_pk_bf16_f32 v253, v55, v56
	v_lshlrev_b32_e32 v57, 16, v220
	v_and_b32_e32 v58, 0xffff0000, v220
	v_lshlrev_b32_e32 v59, 16, v221
	v_and_b32_e32 v60, 0xffff0000, v221
	v_mul_f32_e32 v53, v8, v52
	v_mul_f32_e32 v54, v9, v52
	v_mul_f32_e32 v55, v10, v52
	v_mul_f32_e32 v56, v11, v52
	v_mul_f32_e32 v53, v53, v57
	v_mul_f32_e32 v54, v54, v58
	v_mul_f32_e32 v55, v55, v59
	v_mul_f32_e32 v56, v56, v60
	v_cvt_pk_bf16_f32 v224, v53, v54
	v_cvt_pk_bf16_f32 v225, v55, v56
	v_lshlrev_b32_e32 v57, 16, v222
	v_and_b32_e32 v58, 0xffff0000, v222
	v_lshlrev_b32_e32 v59, 16, v223
	v_and_b32_e32 v60, 0xffff0000, v223
	v_mul_f32_e32 v53, v12, v52
	v_mul_f32_e32 v54, v13, v52
	v_mul_f32_e32 v55, v14, v52
	v_mul_f32_e32 v56, v15, v52
	v_mul_f32_e32 v53, v53, v57
	v_mul_f32_e32 v54, v54, v58
	v_mul_f32_e32 v55, v55, v59
	v_mul_f32_e32 v56, v56, v60
	v_cvt_pk_bf16_f32 v226, v53, v54
	v_cvt_pk_bf16_f32 v227, v55, v56
	s_nop 0
	v_permlane32_swap_b32_e32 v250, v252
	v_permlane32_swap_b32_e32 v251, v253
	v_permlane32_swap_b32_e32 v224, v226
	v_permlane32_swap_b32_e32 v225, v227
	v_bfi_b32 v238, v230, v250, v224
	v_bfi_b32 v239, v230, v251, v225
	v_bfi_b32 v240, v230, v252, v226
	v_bfi_b32 v241, v230, v253, v227
	v_mov_b32_dpp v242, v238 quad_perm:[1,0,3,2] row_mask:0xf bank_mask:0xf
	v_mov_b32_dpp v243, v239 quad_perm:[1,0,3,2] row_mask:0xf bank_mask:0xf
	v_mov_b32_dpp v244, v240 quad_perm:[1,0,3,2] row_mask:0xf bank_mask:0xf
	v_mov_b32_dpp v245, v241 quad_perm:[1,0,3,2] row_mask:0xf bank_mask:0xf
	v_bfi_b32 v250, v230, v242, v250
	v_bfi_b32 v251, v230, v243, v251
	v_bfi_b32 v252, v230, v244, v252
	v_bfi_b32 v253, v230, v245, v253
	v_bfi_b32 v242, v230, v224, v242
	v_bfi_b32 v243, v230, v225, v243
	v_bfi_b32 v244, v230, v226, v244
	v_bfi_b32 v245, v230, v227, v245
	global_store_dwordx4 v[50:51], v[250:253], off offset:-1600
	global_store_dwordx4 v[50:51], v[242:245], off offset:2496
	s_cbranch_scc0 .LBB0_734
